# merge GEMM: start offset of the second workgroup half 1 sleep (about 3.4 us) instead of 2
# baseline (speedup 1.0000x reference)
; #define PG8_STAGE(bufoff, gbase, voff) do { _Pragma("unroll") for (int _i = 0; _i < 2; ++_i) \
;         __builtin_amdgcn_global_load_lds((const unsigned*)((const char*)(gbase) + (voff)[_i]), (LAS unsigned*)(lds + (bufoff) + ldsw + _i * 8192), 16, 0, 0); } while (0)
; #define PG8_BAR __builtin_amdgcn_s_barrier()
; template <class Epi, bool ALIGN_EPI>
; __device__ __forceinline__ void gemm_phase(LAS unsigned char* lds, const int tid, const Gemm g, const StaticOrder& S, const Epi& E) {
;     ...
;     for (int i = 0; i < 2; ++i) { int R, C; stage_rc(tid * 16 + i * 8192, R, C); const int Rb = Epi::PERM ? ((R & ~31) + perm32(R & 31)) : R;
;         voffA[i] = (unsigned)R * rsA + (unsigned)C * 2u; voffB[i] = (unsigned)Rb * rsB + (unsigned)C * 2u; }
;     const size_t hstepA = (size_t)HALF * rsA, hstepB = (size_t)HALF * rsB;
;     const size_t tstepA = 2 * hstepA, tstepB = 2 * hstepB;
;     const unsigned ldsw = (unsigned)wid * 1024u;
;     const int aoff = lds_byte(wr * 64 + fr, fq * 8), boff = lds_byte(wc * 32 + fr, fq * 8);
;     ...
;     const char* cA = (const char*)g.A + (size_t)cur.pm * tstepA + PG8_KOFFA(cur); const char* cB = (const char*)g.Bt + (size_t)cur.pn * tstepB + PG8_KOFFB(cur);
;     PG8_STAGE(PG8_SB(0, 0), cB, voffB); PG8_STAGE(PG8_SB(0, 1), cB + hstepB, voffB); PG8_STAGE(PG8_SA(0, 0), cA, voffA); PG8_STAGE(PG8_SA(0, 1), cA + hstepA, voffA);
;     if (wr == 1) PG8_BAR;
.LBB0_242:
	v_readlane_b32 s100, v249, 56
	s_nop 3
	s_bitcmp1_b32 s100, 3
	s_cbranch_scc0 .Lmerge_nodelay
	s_sleep 127
.Lmerge_nodelay:
	v_bfe_i32 v3, v208, 27, 1
	v_lshlrev_b32_e32 v2, 4, v208
	v_lshrrev_b32_e32 v3, 22, v3
	v_add_u32_e32 v3, v2, v3
	v_and_b32_e32 v3, 0xfffffc00, v3
	v_sub_u32_e32 v3, v2, v3
	v_lshrrev_b32_e32 v4, 4, v3
	v_ashrrev_i32_e32 v0, 31, v208
	v_bitop3_b32 v3, v4, v3, 32 bitop3:0x6c
	s_add_u32 s63, s57, 0x17000000
	v_lshrrev_b32_e32 v0, 26, v0
	v_ashrrev_i32_e32 v5, 31, v3
	s_addc_u32 s64, s49, 0
	s_ashr_i32 s93, s92, 31
	v_add_u32_e32 v0, v208, v0
	v_lshrrev_b32_e32 v5, 26, v5
	s_lshl_b64 s[8:9], s[92:93], 20
	v_ashrrev_i32_e32 v0, 6, v0
	v_add_u32_e32 v5, v3, v5
	s_add_u32 s8, s63, s8
	v_lshlrev_b32_e32 v4, 3, v0
	v_ashrrev_i32_e32 v10, 6, v5
	v_and_b32_e32 v5, 0xc0, v5
	s_addc_u32 s9, s64, s9
	v_readlane_b32 s14, v249, 59
	v_and_b32_e32 v4, -16, v4
	v_sub_u32_e32 v3, v3, v5
	s_add_u32 s65, s14, 0x3100000
	v_readlane_b32 s14, v249, 60
	v_add_u32_e32 v4, v10, v4
	v_ashrrev_i16_sdwa v3, v226, sext(v3) dst_sel:DWORD dst_unused:UNUSED_PAD src0_sel:DWORD src1_sel:BYTE_0
	s_addc_u32 s66, s14, 0
	v_lshlrev_b32_e32 v6, 5, v0
	v_bfe_i32 v11, v3, 0, 16
	v_lshlrev_b32_e32 v3, 1, v4
	v_lshrrev_b32_e32 v5, 2, v4
	v_and_b32_e32 v7, 3, v10
	s_mov_b32 s14, 0xfffe0
	v_and_b32_e32 v6, 32, v6
	v_and_b32_e32 v3, 24, v3
	v_and_b32_e32 v5, 4, v5
	v_and_or_b32 v7, v4, s14, v7
	v_or3_b32 v3, v7, v5, v3
	v_add_lshl_u32 v5, v6, v11, 1
	v_add_u32_e32 v2, 0x2000, v2
	v_lshl_add_u32 v212, v3, 12, v5
	v_ashrrev_i32_e32 v3, 31, v2
	v_lshrrev_b32_e32 v3, 22, v3
	v_add_u32_e32 v3, v2, v3
	v_ashrrev_i32_e32 v12, 10, v3
	v_mul_i32_i24_e32 v3, 0x400, v12
	v_sub_u32_e32 v2, v2, v3
	v_lshrrev_b32_e32 v3, 4, v2
	s_add_u32 s94, s8, s12
	v_bitop3_b32 v2, v3, v2, 32 bitop3:0x6c
	s_addc_u32 s95, s9, s13
	s_ashr_i32 s31, s30, 31
	v_lshl_add_u32 v210, v4, 12, v5
	v_ashrrev_i32_e32 v4, 31, v2
	s_lshl_b64 s[8:9], s[30:31], 20
	v_lshrrev_b32_e32 v4, 26, v4
	s_add_u32 s12, s65, s8
	v_add_u32_e32 v4, v2, v4
	s_addc_u32 s13, s66, s9
	s_ashr_i32 s8, s7, 6
	v_lshlrev_b32_e32 v3, 3, v12
	v_ashrrev_i32_e32 v13, 6, v4
	v_and_b32_e32 v4, 0xc0, v4
	s_ashr_i32 s9, s7, 8
	v_and_b32_e32 v3, -16, v3
	v_sub_u32_e32 v2, v2, v4
	s_lshl_b32 s67, s8, 10
	v_add_u32_e32 v3, v13, v3
	v_ashrrev_i16_sdwa v2, v226, sext(v2) dst_sel:DWORD dst_unused:UNUSED_PAD src0_sel:DWORD src1_sel:BYTE_0
	s_add_u32 s96, s12, s0
	v_lshlrev_b32_e32 v5, 5, v12
	v_bfe_i32 v14, v2, 0, 16
	v_lshlrev_b32_e32 v2, 1, v3
	v_lshrrev_b32_e32 v4, 2, v3
	v_and_b32_e32 v6, 3, v13
	s_addc_u32 s97, s13, s1
	s_add_i32 s68, s67, 0
	v_and_b32_e32 v5, 32, v5
	v_and_b32_e32 v2, 24, v2
	v_and_b32_e32 v4, 4, v4
	v_and_or_b32 v6, v3, s14, v6
	s_add_i32 m0, s68, 0x10000
	v_or3_b32 v2, v6, v4, v2
	v_add_lshl_u32 v4, v5, v14, 1
	global_load_lds_dwordx4 v212, s[96:97]
	s_add_i32 m0, s68, 0x12000
	v_lshl_add_u32 v216, v2, 12, v4
	s_add_u32 s0, s96, 0x80000
	global_load_lds_dwordx4 v216, s[96:97]
	s_addc_u32 s1, s97, 0
	s_add_i32 m0, s68, 0x14000
	s_add_i32 s69, s68, 0x2000
	global_load_lds_dwordx4 v212, s[0:1]
	s_add_i32 m0, s68, 0x16000
	v_lshl_add_u32 v214, v3, 12, v4
	global_load_lds_dwordx4 v216, s[0:1]
	s_mov_b32 m0, s68
	s_add_u32 s0, s94, 0x80000
	global_load_lds_dwordx4 v210, s[94:95]
	s_mov_b32 m0, s69
	s_addc_u32 s1, s95, 0
	s_add_i32 s70, s68, 0x4000
	global_load_lds_dwordx4 v214, s[94:95]
	s_mov_b32 m0, s70
	s_add_i32 s71, s68, 0x6000
	global_load_lds_dwordx4 v210, s[0:1]
	s_mov_b32 m0, s71
	v_mov_b32_e32 v213, v1
	global_load_lds_dwordx4 v214, s[0:1]
	v_mov_b32_e32 v217, v1
	v_mov_b32_e32 v211, v1
	v_mov_b32_e32 v215, v1
	s_cmp_eq_u32 s9, 1
	v_writelane_b32 v248, s16, 5
	s_mov_b32 s81, s56
	v_lshl_add_u64 v[8:9], s[96:97], 0, v[212:213]
	v_lshl_add_u64 v[6:7], s[96:97], 0, v[216:217]
	v_lshl_add_u64 v[2:3], s[94:95], 0, v[210:211]
	s_cselect_b64 s[12:13], -1, 0
	s_cmp_lg_u32 s9, 1
	v_lshl_add_u64 v[4:5], s[94:95], 0, v[214:215]
	v_writelane_b32 v248, s17, 6
	s_cbranch_scc1 .LBB0_244
	s_barrier
